# replace cooperative-groups grid.sync at kernel start by block-0 flag hand-off; census post moved to end of P0
# speedup vs baseline: 1.0112x; 1.0112x over previous
; #define LAS __attribute__((address_space(3)))
; __device__ __forceinline__ unsigned xb_add(unsigned* p, unsigned v) { return __hip_atomic_fetch_add(p, v, __ATOMIC_RELAXED, __HIP_MEMORY_SCOPE_AGENT); }
; __device__ __forceinline__ unsigned xb_xcc_id() { return (unsigned)__builtin_amdgcn_s_getreg((3 << 11) | 20) & 0xFu; }
; __device__ __forceinline__ void transpose_tile(const float* __restrict__ W, int K, int N, bf16* __restrict__ WT, const float* __restrict__ ga, const float* __restrict__ gb, int gsplit, LAS float* scr, int item, int lane) {
;     const int nkb = K / 64, nb = item / nkb, kb = item % nkb, k0 = 64 * kb, n0 = 64 * nb;
; __global__ void __launch_bounds__(NT, 2) fwd_mega(Args A) {
;     ...
;     if (bx == 0) for (int i = tid; i < XCD_BAR_WORDS_ALL; i += NT) barw[i] = 0u;
;     grid.sync();
;     XcdBarrier xbar; xbar.bar = barw; xbar.x = xb_xcc_id(); xbar.st = (volatile LAS unsigned*)(lds + LDS_BARST);
;     if (tid == 0) ((LAS unsigned*)(lds + LDS_BARST))[2] = xb_add(&barw[XB_XCNT(xbar.x)], 1u);
;     {
;         const int gw = vcu * NW + wave, NGW = G * NW;
;         LAS float* scr = (LAS float*)(lds + wave * 16640);
;         constexpr int I_IN = (D / 64) * (INW / 64);
;         for (int it = gw; it < I_IN; it += NGW) transpose_tile(A.w_in, D, INW, WinT, A.g_mix, A.g_mix, D, scr, it, lane);
.LBB0_10:
	s_cmp_lg_u32 s2, 0
	s_mov_b64 s[6:7], exec
	s_cbranch_scc1 .LBB0_20
	s_waitcnt vmcnt(0)
	s_barrier
	v_cmp_eq_u32_e32 vcc, 0, v160
	s_and_saveexec_b64 s[6:7], vcc
	s_cbranch_execz .LBB0_20
	buffer_wbl2 sc1
	s_waitcnt vmcnt(0)
	v_mov_b32_e32 v1, 0x10000
	v_mov_b32_e32 v2, 0x7a3c59e1
	global_store_dword v1, v2, s[34:35] sc0 sc1
.LBB0_20:
	s_or_b64 exec, exec, s[6:7]
	s_load_dwordx16 s[36:51], s[0:1], 0x0
	s_load_dwordx16 s[8:23], s[0:1], 0x40
	s_barrier
	s_waitcnt lgkmcnt(0)
	s_getreg_b32 s0, hwreg(HW_REG_XCC_ID, 0, 4)
	s_and_b32 s33, s0, 15
	v_cmp_eq_u32_e64 s[54:55], 0, v160
	s_nop 1
.LBB0_24:
	v_writelane_b32 v255, s54, 1
	s_nop 1
	v_writelane_b32 v255, s55, 2
	s_add_u32 s54, s28, 0x300000
	s_addc_u32 s55, s29, 0
	s_lshr_b32 s1, s58, 6
	s_lshl_b32 s0, s3, 3
	s_add_i32 s58, s0, s1
	s_mul_i32 s0, s1, 0x4100
	s_lshl_b32 s52, s30, 3
	v_writelane_b32 v255, s1, 3
	s_add_i32 s0, s0, 0
	v_writelane_b32 v255, s0, 4
	s_cmpk_gt_i32 s58, 0x6ff
	v_and_b32_e32 v152, 63, v160
	s_cbranch_scc1 .LBB0_59
	v_and_b32_e32 v0, 15, v160
	v_lshlrev_b32_e32 v0, 4, v0
	v_mov_b32_e32 v1, 0
	v_readlane_b32 s0, v255, 4
	v_lshl_add_u64 v[64:65], s[42:43], 0, v[0:1]
	s_cmp_lg_u64 s[40:41], 0
	v_add_u32_e32 v2, s0, v0
	v_lshlrev_b32_e32 v0, 3, v160
	v_and_b32_e32 v0, 56, v0
	v_lshrrev_b32_e32 v73, 3, v152
	v_mul_u32_u24_e32 v4, 0x104, v0
	v_lshlrev_b32_e32 v0, 1, v0
	v_lshrrev_b32_e32 v72, 4, v152
	s_cselect_b64 s[4:5], -1, 0
	v_lshl_add_u64 v[66:67], s[54:55], 0, v[0:1]
	v_lshlrev_b32_e32 v0, 2, v73
	v_mul_u32_u24_e32 v3, 0x104, v72
	v_add3_u32 v74, s0, v4, v0
	v_cndmask_b32_e64 v0, 0, 1, s[4:5]
	s_movk_i32 s42, 0xe070
	s_movk_i32 s62, 0xe080
	s_movk_i32 s66, 0xe090
	s_movk_i32 s70, 0xe0a0
	s_movk_i32 s74, 0xe0b0
	s_movk_i32 s78, 0xe0c0
	s_movk_i32 s82, 0xe0d0
	s_movk_i32 s86, 0xe0e0
	s_movk_i32 s90, 0xe0f0
	v_or_b32_e32 v75, 8, v73
	v_or_b32_e32 v76, 16, v73
	v_or_b32_e32 v77, 24, v73
	v_or_b32_e32 v78, 32, v73
	v_or_b32_e32 v79, 40, v73
	v_or_b32_e32 v80, 48, v73
	v_or_b32_e32 v81, 56, v73
	s_lshl_b32 s0, s58, 6
	s_lshl_b32 s1, s52, 6
	s_movk_i32 s53, 0x3800
	v_cmp_ne_u32_e64 s[4:5], 1, v0
	s_movk_i32 s59, 0x800
	s_mov_b64 s[6:7], 0x70
	s_mov_b32 s43, -1
	s_mov_b64 s[60:61], 0x80
	s_mov_b32 s63, -1
	s_mov_b64 s[64:65], 0x90
	s_mov_b32 s67, -1
	s_mov_b64 s[68:69], 0xa0
	s_mov_b32 s71, -1
	s_mov_b64 s[72:73], 0xb0
	s_mov_b32 s75, -1
	s_mov_b64 s[76:77], 0xc0
	s_mov_b32 s79, -1
	s_mov_b64 s[80:81], 0xd0
	s_mov_b32 s83, -1
	s_mov_b64 s[84:85], 0xe0
	v_add_u32_e32 v82, v2, v3
	v_mov_b32_e32 v83, 0xffffe000
	s_mov_b32 s96, s58
	s_mov_b32 s87, -1
	s_mov_b64 s[88:89], 0xf0
	s_mov_b32 s91, -1
	s_branch .LBB0_27

; #define LAS __attribute__((address_space(3)))
; __device__ __forceinline__ unsigned xb_ld(unsigned* p)              { return __hip_atomic_load(p, __ATOMIC_RELAXED, __HIP_MEMORY_SCOPE_AGENT); }
; __device__ __forceinline__ unsigned xb_add(unsigned* p, unsigned v) { return __hip_atomic_fetch_add(p, v, __ATOMIC_RELAXED, __HIP_MEMORY_SCOPE_AGENT); }
; __device__ __forceinline__ void xcd_barrier_complete(unsigned* bar, unsigned x, unsigned& nloc, unsigned& nx) {
;     const unsigned G = gridDim.x * gridDim.y * gridDim.z;
;     unsigned sum, cnt, mine, sp = 0u;
;     for (;;) {
;         sum = 0u; cnt = 0u; mine = 0u;
; #pragma unroll
;         for (unsigned j = 0; j < 16; ++j) { const unsigned c = xb_ld(&bar[XB_XCNT(j)]); sum += c; cnt += (c > 0u) ? 1u : 0u; mine = (j == x) ? c : mine; }
;         if (sum == G) break;
;         __builtin_amdgcn_s_sleep(1);
;         if ((++sp & 255u) == 0u) { if (xb_ld(&bar[XB_TMO])) break; if (sp > XB_SPIN_CAP) { atomicAdd(&bar[XB_TMO], 1u); break; } }
;     }
;     nloc = mine > 0u ? mine : 1u; nx = cnt > 0u ? cnt : 1u;
; }
; __device__ __forceinline__ void xcd_barrier(const XcdBarrier& b) {
;     asm volatile("s_waitcnt vmcnt(0)" ::: "memory");
;     __syncthreads();
;     if (threadIdx.x == 0) {
;         unsigned* bar = b.bar;
;         __builtin_amdgcn_s_waitcnt(0);
;         unsigned nloc = b.st[0], nx = b.st[1];
;         if (nloc == 0u) { xcd_barrier_complete(bar, b.x, nloc, nx); b.st[0] = nloc; b.st[1] = nx; }
; __global__ void __launch_bounds__(NT, 2) fwd_mega(Args A) {
;     ...
;     if (tid == 0) ((LAS unsigned*)(lds + LDS_BARST))[2] = xb_add(&barw[XB_XCNT(xbar.x)], 1u);
.LBB0_111:
	s_or_b64 exec, exec, s[8:9]
	s_and_saveexec_b64 s[4:5], s[88:89]
	s_cbranch_execz .Lcs_done
	v_mov_b32_e32 v1, 0x10000
	s_mov_b32 s8, 0x7a3c59e1
	s_mov_b32 s9, 0
.Lgs_spin:
	global_load_dword v2, v1, s[34:35] sc1
	s_waitcnt vmcnt(0)
	v_cmp_ne_u32_e32 vcc, s8, v2
	s_cbranch_vccz .Lgs_ok
	s_sleep 2
	s_add_i32 s9, s9, 1
	s_cmp_lt_u32 s9, 0x100000
	s_cbranch_scc1 .Lgs_spin
.Lgs_ok:
	buffer_inv sc1
	s_waitcnt vmcnt(0)
	s_lshl_b32 s0, s33, 8
	v_mov_b32_e32 v1, s0
	v_mov_b32_e32 v2, 1
	global_atomic_add v1, v1, v2, s[34:35] offset:1024 sc0
	s_waitcnt vmcnt(0)
	v_mov_b32_e32 v0, 0x23fc8
	ds_write_b32 v0, v1
.Lcs_done:
	s_or_b64 exec, exec, s[4:5]
	s_waitcnt vmcnt(0)
	s_waitcnt lgkmcnt(0)
	s_barrier
	s_and_saveexec_b64 s[4:5], s[88:89]
	s_cbranch_execz .LBB0_164
	s_add_i32 s0, 0, 0x23fc0
	v_mov_b32_e32 v0, s0
	s_waitcnt vmcnt(0) expcnt(0) lgkmcnt(0)
	ds_read_b32 v2, v0
	s_add_i32 s0, 0, 0x23fc4
	v_mov_b32_e32 v0, s0
	ds_read_b32 v0, v0
	s_waitcnt lgkmcnt(1)
	v_cmp_ne_u32_e32 vcc, 0, v2
	s_cbranch_vccnz .LBB0_128
	s_add_u32 s6, s28, 0x210200
	s_addc_u32 s7, s29, 0
	s_add_u32 s8, s28, 0x210400
	s_addc_u32 s9, s29, 0
	s_add_u32 s10, s28, 0x210500
	s_addc_u32 s11, s29, 0
	s_add_u32 s12, s28, 0x210600
	s_addc_u32 s13, s29, 0
	s_add_u32 s36, s28, 0x210700
	s_addc_u32 s37, s29, 0
	s_add_u32 s40, s28, 0x210800
	s_addc_u32 s41, s29, 0
	s_add_u32 s42, s28, 0x210900
	s_addc_u32 s43, s29, 0
	s_add_u32 s44, s28, 0x210a00
	s_addc_u32 s45, s29, 0
	s_add_u32 s46, s28, 0x210b00
	s_addc_u32 s47, s29, 0
	s_add_u32 s48, s28, 0x210c00
	s_addc_u32 s49, s29, 0
	s_add_u32 s50, s28, 0x210d00
	s_addc_u32 s51, s29, 0
	s_add_u32 s58, s28, 0x210e00
	s_addc_u32 s59, s29, 0
	s_add_u32 s60, s28, 0x210f00
	s_addc_u32 s61, s29, 0
	s_add_u32 s62, s28, 0x211000
	s_addc_u32 s63, s29, 0
	s_add_u32 s64, s28, 0x211100
	s_addc_u32 s65, s29, 0
	s_add_u32 s66, s28, 0x211200
	v_readlane_b32 s0, v255, 0
	s_addc_u32 s67, s29, 0
	s_mul_i32 s0, s31, s0
	s_add_u32 s68, s28, 0x211300
	s_mul_i32 s0, s0, s30
	s_addc_u32 s69, s29, 0
	s_mov_b32 s1, 1
	v_mov_b32_e32 v16, 0
	s_branch .LBB0_115

; #define LAS __attribute__((address_space(3)))
; __device__ __forceinline__ unsigned xb_ld(unsigned* p)              { return __hip_atomic_load(p, __ATOMIC_RELAXED, __HIP_MEMORY_SCOPE_AGENT); }
; __global__ void __launch_bounds__(NT, 2) fwd_mega(Args A) {
;     ...
;     if (tid == 0) {
;         bool ok = (G % 8 == 0);
;         for (unsigned j = 0; j < 16; ++j) { const unsigned cj = xb_ld(&barw[XB_XCNT(j)]); ok = ok && ((j < 8) ? (cj == (unsigned)(G / 8)) : (cj == 0u)); }
;         LAS unsigned* st = (LAS unsigned*)(lds + LDS_BARST); st[3] = ok ? (st[2] * 8u + xbar.x) : (unsigned)bx; st[4] = ok ? 1u : 0u;
;     }
.LBB0_164:
	s_or_b64 exec, exec, s[4:5]
	s_waitcnt lgkmcnt(0)
	s_barrier
	s_cmp_lg_u32 s2, 0
	s_cbranch_scc1 .Lgs_noclr
	s_and_saveexec_b64 s[4:5], s[88:89]
	v_mov_b32_e32 v0, 0x10000
	v_mov_b32_e32 v1, 0
	global_store_dword v0, v1, s[34:35] sc0 sc1
	s_or_b64 exec, exec, s[4:5]
.Lgs_noclr:
	s_and_saveexec_b64 s[4:5], s[88:89]
	s_cbranch_execz .LBB0_224
	v_mov_b32_e32 v1, 0x210000
	global_load_dword v2, v1, s[28:29] offset:1024 sc1
	global_load_dword v0, v1, s[28:29] offset:1280 sc1
	s_ashr_i32 s0, s30, 31
	s_lshr_b32 s0, s0, 29
	s_add_i32 s0, s30, s0
	s_ashr_i32 s0, s0, 3
	s_mov_b64 s[6:7], -1
	s_mov_b64 s[8:9], 0
	s_waitcnt vmcnt(1)
	v_cmp_eq_u32_e32 vcc, s0, v2
	s_and_b64 s[10:11], s[56:57], vcc
	s_andn2_b64 vcc, exec, s[10:11]
	s_mov_b64 s[10:11], 0
	s_cbranch_vccz .LBB0_167
	global_load_dword v1, v1, s[28:29] offset:1536 sc1
	s_mov_b64 s[6:7], 0
	s_mov_b64 s[10:11], -1

;     __device__ __forceinline__ void operator()(const f32x4 (&acc)[2][2][4][2], const Unit& u, int wr, int wc, int fr, int fq) const {
;         const int row0 = u.pm * BM + wr * 64 + fr, col0 = u.pn * BM + wc * 32 + 4 * fq;
; #pragma unroll
;         for (int ai = 0; ai < 2; ++ai)
; #pragma unroll
;             for (int m = 0; m < 4; ++m) {
;                 const size_t off = (size_t)(row0 + ai * HALF + m * 16) * DM + col0;
; #pragma unroll
;                 for (int bj = 0; bj < 2; ++bj)
; #pragma unroll
;                     for (int n = 0; n < 2; ++n) { const u32x2 xw = *(const u32x2*)(x1b + off + bj * HALF + n * 16); f32x4 v = acc[ai][bj][m][n];
;                         v[0] += __builtin_bit_cast(float, xw.x << 16); v[1] += __builtin_bit_cast(float, xw.x & 0xffff0000u); v[2] += __builtin_bit_cast(float, xw.y << 16); v[3] += __builtin_bit_cast(float, xw.y & 0xffff0000u);
;                         __builtin_nontemporal_store(v, (f32x4*)(out + off + bj * HALF + n * 16)); }
;             }
;     }
.LBB0_964:
	v_lshl_add_u32 v144, s54, 8, v146
	v_lshl_or_b32 v142, s0, 8, v148
	v_ashrrev_i32_e32 v145, 31, v144
	v_ashrrev_i32_e32 v143, 31, v142
	v_lshlrev_b64 v[140:141], 11, v[144:145]
	v_lshl_add_u64 v[140:141], v[140:141], 0, v[142:143]
	v_lshl_add_u64 v[152:153], v[140:141], 1, s[36:37]
	global_load_dwordx2 v[154:155], v[152:153], off
	v_lshl_add_u64 v[156:157], v[140:141], 2, s[26:27]
	s_andn2_b64 vcc, exec, s[4:5]
	s_mov_b64 s[4:5], -1
	s_waitcnt vmcnt(0)
	v_lshlrev_b32_e32 v158, 16, v154
	v_and_b32_e32 v159, 0xffff0000, v154
	v_lshlrev_b32_e32 v154, 16, v155
	v_and_b32_e32 v155, 0xffff0000, v155
	v_pk_add_f32 v[124:125], v[124:125], v[158:159]
	v_pk_add_f32 v[126:127], v[126:127], v[154:155]
	global_store_dwordx4 v[156:157], v[124:127], off nt
	global_load_dwordx2 v[124:125], v[152:153], off offset:32
	s_waitcnt vmcnt(0)
	v_lshlrev_b32_e32 v126, 16, v124
	v_and_b32_e32 v127, 0xffff0000, v124
	v_lshlrev_b32_e32 v124, 16, v125
	v_and_b32_e32 v125, 0xffff0000, v125
	v_pk_add_f32 v[120:121], v[120:121], v[126:127]
	v_pk_add_f32 v[122:123], v[122:123], v[124:125]
	global_store_dwordx4 v[156:157], v[120:123], off offset:64 nt
	global_load_dwordx2 v[120:121], v[152:153], off offset:256
	s_waitcnt vmcnt(0)
	v_lshlrev_b32_e32 v122, 16, v120
	v_and_b32_e32 v123, 0xffff0000, v120
	v_lshlrev_b32_e32 v120, 16, v121
	v_and_b32_e32 v121, 0xffff0000, v121
	v_pk_add_f32 v[116:117], v[116:117], v[122:123]
	v_pk_add_f32 v[118:119], v[118:119], v[120:121]
	global_store_dwordx4 v[156:157], v[116:119], off offset:512 nt
	global_load_dwordx2 v[116:117], v[152:153], off offset:288
	s_waitcnt vmcnt(0)
	v_lshlrev_b32_e32 v122, 16, v116
	v_or_b32_e32 v118, 16, v144
	v_ashrrev_i32_e32 v119, 31, v118
	v_lshlrev_b64 v[118:119], 11, v[118:119]
	v_and_b32_e32 v123, 0xffff0000, v116
	v_lshlrev_b32_e32 v116, 16, v117
	v_and_b32_e32 v117, 0xffff0000, v117
	v_lshl_add_u64 v[118:119], v[118:119], 0, v[142:143]
	v_pk_add_f32 v[108:109], v[108:109], v[122:123]
	v_pk_add_f32 v[110:111], v[110:111], v[116:117]
	v_lshl_add_u64 v[120:121], v[118:119], 1, s[36:37]
	global_store_dwordx4 v[156:157], v[108:111], off offset:576 nt
	global_load_dwordx2 v[108:109], v[120:121], off
	v_lshl_add_u64 v[116:117], v[118:119], 2, s[26:27]
	s_waitcnt vmcnt(0)
	v_lshlrev_b32_e32 v110, 16, v108
	v_and_b32_e32 v111, 0xffff0000, v108
	v_lshlrev_b32_e32 v118, 16, v109
	v_and_b32_e32 v119, 0xffff0000, v109
	v_pk_add_f32 v[108:109], v[112:113], v[110:111]
	v_pk_add_f32 v[110:111], v[114:115], v[118:119]
	global_store_dwordx4 v[116:117], v[108:111], off nt
	global_load_dwordx2 v[108:109], v[120:121], off offset:32
	s_waitcnt vmcnt(0)
	v_lshlrev_b32_e32 v110, 16, v108
	v_and_b32_e32 v111, 0xffff0000, v108
	v_lshlrev_b32_e32 v108, 16, v109
	v_and_b32_e32 v109, 0xffff0000, v109
	v_pk_add_f32 v[104:105], v[104:105], v[110:111]
	v_pk_add_f32 v[106:107], v[106:107], v[108:109]
	global_store_dwordx4 v[116:117], v[104:107], off offset:64 nt
	global_load_dwordx2 v[104:105], v[120:121], off offset:256
	s_waitcnt vmcnt(0)
	v_lshlrev_b32_e32 v106, 16, v104
	v_and_b32_e32 v107, 0xffff0000, v104
	v_lshlrev_b32_e32 v104, 16, v105
	v_and_b32_e32 v105, 0xffff0000, v105
	v_pk_add_f32 v[100:101], v[100:101], v[106:107]
	v_pk_add_f32 v[102:103], v[102:103], v[104:105]
	global_store_dwordx4 v[116:117], v[100:103], off offset:512 nt
	global_load_dwordx2 v[100:101], v[120:121], off offset:288
	s_waitcnt vmcnt(0)
	v_lshlrev_b32_e32 v106, 16, v100
	v_or_b32_e32 v102, 32, v144
	v_ashrrev_i32_e32 v103, 31, v102
	v_lshlrev_b64 v[102:103], 11, v[102:103]
	v_and_b32_e32 v107, 0xffff0000, v100
	v_lshlrev_b32_e32 v100, 16, v101
	v_and_b32_e32 v101, 0xffff0000, v101
	v_lshl_add_u64 v[102:103], v[102:103], 0, v[142:143]
	v_pk_add_f32 v[92:93], v[92:93], v[106:107]
	v_pk_add_f32 v[94:95], v[94:95], v[100:101]
	v_lshl_add_u64 v[104:105], v[102:103], 1, s[36:37]
	global_store_dwordx4 v[116:117], v[92:95], off offset:576 nt
	global_load_dwordx2 v[92:93], v[104:105], off
	v_lshl_add_u64 v[100:101], v[102:103], 2, s[26:27]
	s_waitcnt vmcnt(0)
	v_lshlrev_b32_e32 v94, 16, v92
	v_and_b32_e32 v95, 0xffff0000, v92
	v_lshlrev_b32_e32 v102, 16, v93
	v_and_b32_e32 v103, 0xffff0000, v93
	v_pk_add_f32 v[92:93], v[96:97], v[94:95]
	v_pk_add_f32 v[94:95], v[98:99], v[102:103]
	global_store_dwordx4 v[100:101], v[92:95], off nt
	global_load_dwordx2 v[92:93], v[104:105], off offset:32
	s_waitcnt vmcnt(0)
	v_lshlrev_b32_e32 v94, 16, v92
	v_and_b32_e32 v95, 0xffff0000, v92
	v_lshlrev_b32_e32 v92, 16, v93
	v_and_b32_e32 v93, 0xffff0000, v93
	v_pk_add_f32 v[88:89], v[88:89], v[94:95]
	v_pk_add_f32 v[90:91], v[90:91], v[92:93]
	global_store_dwordx4 v[100:101], v[88:91], off offset:64 nt
	global_load_dwordx2 v[88:89], v[104:105], off offset:256
	s_waitcnt vmcnt(0)
	v_lshlrev_b32_e32 v90, 16, v88
	v_and_b32_e32 v91, 0xffff0000, v88
	v_lshlrev_b32_e32 v88, 16, v89
	v_and_b32_e32 v89, 0xffff0000, v89
	v_pk_add_f32 v[84:85], v[84:85], v[90:91]
	v_pk_add_f32 v[86:87], v[86:87], v[88:89]
	global_store_dwordx4 v[100:101], v[84:87], off offset:512 nt
	global_load_dwordx2 v[84:85], v[104:105], off offset:288
	s_waitcnt vmcnt(0)
	v_lshlrev_b32_e32 v90, 16, v84
	v_or_b32_e32 v86, 48, v144
	v_ashrrev_i32_e32 v87, 31, v86
	v_lshlrev_b64 v[86:87], 11, v[86:87]
	v_and_b32_e32 v91, 0xffff0000, v84
	v_lshlrev_b32_e32 v84, 16, v85
	v_and_b32_e32 v85, 0xffff0000, v85
	v_lshl_add_u64 v[86:87], v[86:87], 0, v[142:143]
	v_pk_add_f32 v[76:77], v[76:77], v[90:91]
	v_pk_add_f32 v[78:79], v[78:79], v[84:85]
	v_lshl_add_u64 v[88:89], v[86:87], 1, s[36:37]
	global_store_dwordx4 v[100:101], v[76:79], off offset:576 nt
	global_load_dwordx2 v[76:77], v[88:89], off
	v_lshl_add_u64 v[84:85], v[86:87], 2, s[26:27]
	s_waitcnt vmcnt(0)
;     __device__ __forceinline__ void operator()(const f32x4 (&acc)[2][2][4][2], const Unit& u, int wr, int wc, int fr, int fq) const {
;         const int row0 = u.pm * BM + wr * 64 + fr, col0 = u.pn * BM + wc * 32 + 4 * fq;
; #pragma unroll
;         for (int ai = 0; ai < 2; ++ai)
; #pragma unroll
;             for (int m = 0; m < 4; ++m) {
;                 const size_t off = (size_t)(row0 + ai * HALF + m * 16) * DM + col0;
; #pragma unroll
;                 for (int bj = 0; bj < 2; ++bj)
; #pragma unroll
;                     for (int n = 0; n < 2; ++n) { const u32x2 xw = *(const u32x2*)(x1b + off + bj * HALF + n * 16); f32x4 v = acc[ai][bj][m][n];
;                         v[0] += __builtin_bit_cast(float, xw.x << 16); v[1] += __builtin_bit_cast(float, xw.x & 0xffff0000u); v[2] += __builtin_bit_cast(float, xw.y << 16); v[3] += __builtin_bit_cast(float, xw.y & 0xffff0000u);
;                         __builtin_nontemporal_store(v, (f32x4*)(out + off + bj * HALF + n * 16)); }
;             }
;     }
	v_lshlrev_b32_e32 v78, 16, v76
	v_and_b32_e32 v79, 0xffff0000, v76
	v_lshlrev_b32_e32 v86, 16, v77
	v_and_b32_e32 v87, 0xffff0000, v77
	v_pk_add_f32 v[76:77], v[80:81], v[78:79]
	v_pk_add_f32 v[78:79], v[82:83], v[86:87]
	global_store_dwordx4 v[84:85], v[76:79], off nt
	global_load_dwordx2 v[76:77], v[88:89], off offset:32
	s_waitcnt vmcnt(0)
	v_lshlrev_b32_e32 v78, 16, v76
	v_and_b32_e32 v79, 0xffff0000, v76
	v_lshlrev_b32_e32 v76, 16, v77
	v_and_b32_e32 v77, 0xffff0000, v77
	v_pk_add_f32 v[72:73], v[72:73], v[78:79]
	v_pk_add_f32 v[74:75], v[74:75], v[76:77]
	global_store_dwordx4 v[84:85], v[72:75], off offset:64 nt
	global_load_dwordx2 v[72:73], v[88:89], off offset:256
	s_waitcnt vmcnt(0)
	v_lshlrev_b32_e32 v74, 16, v72
	v_and_b32_e32 v75, 0xffff0000, v72
	v_lshlrev_b32_e32 v72, 16, v73
	v_and_b32_e32 v73, 0xffff0000, v73
	v_pk_add_f32 v[68:69], v[68:69], v[74:75]
	v_pk_add_f32 v[70:71], v[70:71], v[72:73]
	global_store_dwordx4 v[84:85], v[68:71], off offset:512 nt
	global_load_dwordx2 v[68:69], v[88:89], off offset:288
	s_waitcnt vmcnt(0)
	v_lshlrev_b32_e32 v74, 16, v68
	v_and_b32_e32 v75, 0xffff0000, v68
	v_lshlrev_b32_e32 v68, 16, v69
	v_and_b32_e32 v69, 0xffff0000, v69
	v_lshl_add_u64 v[70:71], v[140:141], 0, s[38:39]
	v_pk_add_f32 v[64:65], v[64:65], v[74:75]
	v_pk_add_f32 v[66:67], v[66:67], v[68:69]
	v_lshl_add_u64 v[72:73], v[70:71], 1, s[36:37]
	global_store_dwordx4 v[84:85], v[64:67], off offset:576 nt
	global_load_dwordx2 v[64:65], v[72:73], off
	s_waitcnt vmcnt(0)
	v_lshlrev_b32_e32 v68, 16, v64
	v_and_b32_e32 v69, 0xffff0000, v64
	v_lshlrev_b32_e32 v64, 16, v65
	v_and_b32_e32 v65, 0xffff0000, v65
	v_lshl_add_u64 v[66:67], v[70:71], 2, s[26:27]
	v_pk_add_f32 v[60:61], v[60:61], v[68:69]
	v_pk_add_f32 v[62:63], v[62:63], v[64:65]
	global_store_dwordx4 v[66:67], v[60:63], off nt
	global_load_dwordx2 v[60:61], v[72:73], off offset:32
	s_waitcnt vmcnt(0)
	v_lshlrev_b32_e32 v62, 16, v60
	v_and_b32_e32 v63, 0xffff0000, v60
	v_lshlrev_b32_e32 v60, 16, v61
	v_and_b32_e32 v61, 0xffff0000, v61
	v_pk_add_f32 v[56:57], v[56:57], v[62:63]
	v_pk_add_f32 v[58:59], v[58:59], v[60:61]
	global_store_dwordx4 v[66:67], v[56:59], off offset:64 nt
	global_load_dwordx2 v[56:57], v[72:73], off offset:256
	s_waitcnt vmcnt(0)
	v_lshlrev_b32_e32 v58, 16, v56
	v_and_b32_e32 v59, 0xffff0000, v56
	v_lshlrev_b32_e32 v56, 16, v57
	v_and_b32_e32 v57, 0xffff0000, v57
	v_pk_add_f32 v[52:53], v[52:53], v[58:59]
	v_pk_add_f32 v[54:55], v[54:55], v[56:57]
	global_store_dwordx4 v[66:67], v[52:55], off offset:512 nt
	global_load_dwordx2 v[52:53], v[72:73], off offset:288
	s_waitcnt vmcnt(0)
	v_lshlrev_b32_e32 v58, 16, v52
	v_and_b32_e32 v59, 0xffff0000, v52
	v_lshlrev_b32_e32 v52, 16, v53
	v_and_b32_e32 v53, 0xffff0000, v53
	v_lshl_add_u64 v[54:55], v[140:141], 0, s[40:41]
	v_pk_add_f32 v[44:45], v[44:45], v[58:59]
	v_pk_add_f32 v[46:47], v[46:47], v[52:53]
	v_lshl_add_u64 v[56:57], v[54:55], 1, s[36:37]
	global_store_dwordx4 v[66:67], v[44:47], off offset:576 nt
	global_load_dwordx2 v[44:45], v[56:57], off
	v_lshl_add_u64 v[52:53], v[54:55], 2, s[26:27]
	s_waitcnt vmcnt(0)
	v_lshlrev_b32_e32 v46, 16, v44
	v_and_b32_e32 v47, 0xffff0000, v44
	v_lshlrev_b32_e32 v54, 16, v45
	v_and_b32_e32 v55, 0xffff0000, v45
	v_pk_add_f32 v[44:45], v[48:49], v[46:47]
	v_pk_add_f32 v[46:47], v[50:51], v[54:55]
	global_store_dwordx4 v[52:53], v[44:47], off nt
	global_load_dwordx2 v[44:45], v[56:57], off offset:32
	s_waitcnt vmcnt(0)
	v_lshlrev_b32_e32 v46, 16, v44
	v_and_b32_e32 v47, 0xffff0000, v44
	v_lshlrev_b32_e32 v44, 16, v45
	v_and_b32_e32 v45, 0xffff0000, v45
	v_pk_add_f32 v[40:41], v[40:41], v[46:47]
	v_pk_add_f32 v[42:43], v[42:43], v[44:45]
	global_store_dwordx4 v[52:53], v[40:43], off offset:64 nt
	global_load_dwordx2 v[40:41], v[56:57], off offset:256
	s_waitcnt vmcnt(0)
;     __device__ __forceinline__ void operator()(const f32x4 (&acc)[2][2][4][2], const Unit& u, int wr, int wc, int fr, int fq) const {
;         const int row0 = u.pm * BM + wr * 64 + fr, col0 = u.pn * BM + wc * 32 + 4 * fq;
; #pragma unroll
;         for (int ai = 0; ai < 2; ++ai)
; #pragma unroll
;             for (int m = 0; m < 4; ++m) {
;                 const size_t off = (size_t)(row0 + ai * HALF + m * 16) * DM + col0;
; #pragma unroll
;                 for (int bj = 0; bj < 2; ++bj)
; #pragma unroll
;                     for (int n = 0; n < 2; ++n) { const u32x2 xw = *(const u32x2*)(x1b + off + bj * HALF + n * 16); f32x4 v = acc[ai][bj][m][n];
;                         v[0] += __builtin_bit_cast(float, xw.x << 16); v[1] += __builtin_bit_cast(float, xw.x & 0xffff0000u); v[2] += __builtin_bit_cast(float, xw.y << 16); v[3] += __builtin_bit_cast(float, xw.y & 0xffff0000u);
;                         __builtin_nontemporal_store(v, (f32x4*)(out + off + bj * HALF + n * 16)); }
;             }
;     }
	v_lshlrev_b32_e32 v42, 16, v40
	v_and_b32_e32 v43, 0xffff0000, v40
	v_lshlrev_b32_e32 v40, 16, v41
	v_and_b32_e32 v41, 0xffff0000, v41
	v_pk_add_f32 v[36:37], v[36:37], v[42:43]
	v_pk_add_f32 v[38:39], v[38:39], v[40:41]
	global_store_dwordx4 v[52:53], v[36:39], off offset:512 nt
	global_load_dwordx2 v[36:37], v[56:57], off offset:288
	s_waitcnt vmcnt(0)
	v_lshlrev_b32_e32 v42, 16, v36
	v_and_b32_e32 v43, 0xffff0000, v36
	v_lshlrev_b32_e32 v36, 16, v37
	v_and_b32_e32 v37, 0xffff0000, v37
	v_lshl_add_u64 v[38:39], v[140:141], 0, s[42:43]
	v_pk_add_f32 v[28:29], v[28:29], v[42:43]
	v_pk_add_f32 v[30:31], v[30:31], v[36:37]
	v_lshl_add_u64 v[40:41], v[38:39], 1, s[36:37]
	global_store_dwordx4 v[52:53], v[28:31], off offset:576 nt
	global_load_dwordx2 v[28:29], v[40:41], off
	v_lshl_add_u64 v[36:37], v[38:39], 2, s[26:27]
	s_waitcnt vmcnt(0)
	v_lshlrev_b32_e32 v30, 16, v28
	v_and_b32_e32 v31, 0xffff0000, v28
	v_lshlrev_b32_e32 v38, 16, v29
	v_and_b32_e32 v39, 0xffff0000, v29
	v_pk_add_f32 v[28:29], v[32:33], v[30:31]
	v_pk_add_f32 v[30:31], v[34:35], v[38:39]
	global_store_dwordx4 v[36:37], v[28:31], off nt
	global_load_dwordx2 v[28:29], v[40:41], off offset:32
	s_waitcnt vmcnt(0)
	v_lshlrev_b32_e32 v30, 16, v28
	v_and_b32_e32 v31, 0xffff0000, v28
	v_lshlrev_b32_e32 v28, 16, v29
	v_and_b32_e32 v29, 0xffff0000, v29
	v_pk_add_f32 v[24:25], v[24:25], v[30:31]
	v_pk_add_f32 v[26:27], v[26:27], v[28:29]
	global_store_dwordx4 v[36:37], v[24:27], off offset:64 nt
	global_load_dwordx2 v[24:25], v[40:41], off offset:256
	s_waitcnt vmcnt(0)
	v_lshlrev_b32_e32 v26, 16, v24
	v_and_b32_e32 v27, 0xffff0000, v24
	v_lshlrev_b32_e32 v24, 16, v25
	v_and_b32_e32 v25, 0xffff0000, v25
	v_pk_add_f32 v[20:21], v[20:21], v[26:27]
	v_pk_add_f32 v[22:23], v[22:23], v[24:25]
	global_store_dwordx4 v[36:37], v[20:23], off offset:512 nt
	global_load_dwordx2 v[20:21], v[40:41], off offset:288
	s_waitcnt vmcnt(0)
	v_lshlrev_b32_e32 v26, 16, v20
	v_and_b32_e32 v27, 0xffff0000, v20
	v_lshlrev_b32_e32 v20, 16, v21
	v_and_b32_e32 v21, 0xffff0000, v21
	v_lshl_add_u64 v[22:23], v[140:141], 0, s[44:45]
	v_pk_add_f32 v[12:13], v[12:13], v[26:27]
	v_pk_add_f32 v[14:15], v[14:15], v[20:21]
	v_lshl_add_u64 v[24:25], v[22:23], 1, s[36:37]
	global_store_dwordx4 v[36:37], v[12:15], off offset:576 nt
	global_load_dwordx2 v[12:13], v[24:25], off
	v_lshl_add_u64 v[20:21], v[22:23], 2, s[26:27]
	s_waitcnt vmcnt(0)
	v_lshlrev_b32_e32 v14, 16, v12
	v_and_b32_e32 v15, 0xffff0000, v12
	v_lshlrev_b32_e32 v22, 16, v13
	v_and_b32_e32 v23, 0xffff0000, v13
	v_pk_add_f32 v[12:13], v[16:17], v[14:15]
	v_pk_add_f32 v[14:15], v[18:19], v[22:23]
	global_store_dwordx4 v[20:21], v[12:15], off nt
	global_load_dwordx2 v[12:13], v[24:25], off offset:32
	s_waitcnt vmcnt(0)
	v_lshlrev_b32_e32 v14, 16, v12
	v_and_b32_e32 v15, 0xffff0000, v12
	v_lshlrev_b32_e32 v12, 16, v13
	v_and_b32_e32 v13, 0xffff0000, v13
	v_pk_add_f32 v[8:9], v[8:9], v[14:15]
	v_pk_add_f32 v[10:11], v[10:11], v[12:13]
	global_store_dwordx4 v[20:21], v[8:11], off offset:64 nt
	global_load_dwordx2 v[8:9], v[24:25], off offset:256
	s_waitcnt vmcnt(0)
	v_lshlrev_b32_e32 v10, 16, v8
	v_and_b32_e32 v11, 0xffff0000, v8
	v_lshlrev_b32_e32 v8, 16, v9
	v_and_b32_e32 v9, 0xffff0000, v9
	v_pk_add_f32 v[4:5], v[4:5], v[10:11]
	v_pk_add_f32 v[6:7], v[6:7], v[8:9]
	global_store_dwordx4 v[20:21], v[4:7], off offset:512 nt
	global_load_dwordx2 v[4:5], v[24:25], off offset:288
	s_waitcnt vmcnt(0)
	v_lshlrev_b32_e32 v6, 16, v4
	v_and_b32_e32 v7, 0xffff0000, v4
	v_lshlrev_b32_e32 v4, 16, v5
	v_and_b32_e32 v5, 0xffff0000, v5
	v_pk_add_f32 v[0:1], v[0:1], v[6:7]
	v_pk_add_f32 v[2:3], v[2:3], v[4:5]
	global_store_dwordx4 v[20:21], v[0:3], off offset:576 nt
	s_cbranch_vccnz .LBB0_953
	s_andn2_b64 vcc, exec, s[20:21]
	s_cbranch_vccnz .LBB0_952
	s_barrier
	s_branch .LBB0_952

;     __device__ __forceinline__ void operator()(const f32x4 (&acc)[2][2][4][2], const Unit& u, int wr, int wc, int fr, int fq) const {
;         const int row0 = u.pm * BM + wr * 64 + fr, col0 = u.pn * BM + wc * 32 + 4 * fq;
; #pragma unroll
;         for (int ai = 0; ai < 2; ++ai)
; #pragma unroll
;             for (int m = 0; m < 4; ++m) {
;                 const size_t off = (size_t)(row0 + ai * HALF + m * 16) * DM + col0;
; #pragma unroll
;                 for (int bj = 0; bj < 2; ++bj)
; #pragma unroll
;                     for (int n = 0; n < 2; ++n) { const u32x2 xw = *(const u32x2*)(x1b + off + bj * HALF + n * 16); f32x4 v = acc[ai][bj][m][n];
;                         v[0] += __builtin_bit_cast(float, xw.x << 16); v[1] += __builtin_bit_cast(float, xw.x & 0xffff0000u); v[2] += __builtin_bit_cast(float, xw.y << 16); v[3] += __builtin_bit_cast(float, xw.y & 0xffff0000u);
;                         __builtin_nontemporal_store(v, (f32x4*)(out + off + bj * HALF + n * 16)); }
;             }
;     }
.LBB0_1164:
	v_lshl_add_u32 v144, s34, 8, v146
	v_lshl_or_b32 v142, s50, 8, v148
	v_ashrrev_i32_e32 v145, 31, v144
	v_ashrrev_i32_e32 v143, 31, v142
	v_lshlrev_b64 v[140:141], 11, v[144:145]
	v_lshl_add_u64 v[140:141], v[140:141], 0, v[142:143]
	v_lshl_add_u64 v[152:153], v[140:141], 1, s[20:21]
	global_load_dwordx2 v[154:155], v[152:153], off
	v_lshl_add_u64 v[156:157], v[140:141], 2, s[4:5]
	s_andn2_b64 vcc, exec, s[0:1]
	s_mov_b64 s[0:1], -1
	s_waitcnt vmcnt(0)
	v_lshlrev_b32_e32 v158, 16, v154
	v_and_b32_e32 v159, 0xffff0000, v154
	v_lshlrev_b32_e32 v154, 16, v155
	v_and_b32_e32 v155, 0xffff0000, v155
	v_pk_add_f32 v[124:125], v[124:125], v[158:159]
	v_pk_add_f32 v[126:127], v[126:127], v[154:155]
	global_store_dwordx4 v[156:157], v[124:127], off nt
	global_load_dwordx2 v[124:125], v[152:153], off offset:32
	s_waitcnt vmcnt(0)
	v_lshlrev_b32_e32 v126, 16, v124
	v_and_b32_e32 v127, 0xffff0000, v124
	v_lshlrev_b32_e32 v124, 16, v125
	v_and_b32_e32 v125, 0xffff0000, v125
	v_pk_add_f32 v[120:121], v[120:121], v[126:127]
	v_pk_add_f32 v[122:123], v[122:123], v[124:125]
	global_store_dwordx4 v[156:157], v[120:123], off offset:64 nt
	global_load_dwordx2 v[120:121], v[152:153], off offset:256
	s_waitcnt vmcnt(0)
	v_lshlrev_b32_e32 v122, 16, v120
	v_and_b32_e32 v123, 0xffff0000, v120
	v_lshlrev_b32_e32 v120, 16, v121
	v_and_b32_e32 v121, 0xffff0000, v121
	v_pk_add_f32 v[116:117], v[116:117], v[122:123]
	v_pk_add_f32 v[118:119], v[118:119], v[120:121]
	global_store_dwordx4 v[156:157], v[116:119], off offset:512 nt
	global_load_dwordx2 v[116:117], v[152:153], off offset:288
	s_waitcnt vmcnt(0)
	v_lshlrev_b32_e32 v122, 16, v116
	v_or_b32_e32 v118, 16, v144
	v_ashrrev_i32_e32 v119, 31, v118
	v_lshlrev_b64 v[118:119], 11, v[118:119]
	v_and_b32_e32 v123, 0xffff0000, v116
	v_lshlrev_b32_e32 v116, 16, v117
	v_and_b32_e32 v117, 0xffff0000, v117
	v_lshl_add_u64 v[118:119], v[118:119], 0, v[142:143]
	v_pk_add_f32 v[108:109], v[108:109], v[122:123]
	v_pk_add_f32 v[110:111], v[110:111], v[116:117]
	v_lshl_add_u64 v[120:121], v[118:119], 1, s[20:21]
	global_store_dwordx4 v[156:157], v[108:111], off offset:576 nt
	global_load_dwordx2 v[108:109], v[120:121], off
	v_lshl_add_u64 v[116:117], v[118:119], 2, s[4:5]
	s_waitcnt vmcnt(0)
	v_lshlrev_b32_e32 v110, 16, v108
	v_and_b32_e32 v111, 0xffff0000, v108
	v_lshlrev_b32_e32 v118, 16, v109
	v_and_b32_e32 v119, 0xffff0000, v109
	v_pk_add_f32 v[108:109], v[112:113], v[110:111]
	v_pk_add_f32 v[110:111], v[114:115], v[118:119]
	global_store_dwordx4 v[116:117], v[108:111], off nt
	global_load_dwordx2 v[108:109], v[120:121], off offset:32
	s_waitcnt vmcnt(0)
	v_lshlrev_b32_e32 v110, 16, v108
	v_and_b32_e32 v111, 0xffff0000, v108
	v_lshlrev_b32_e32 v108, 16, v109
	v_and_b32_e32 v109, 0xffff0000, v109
	v_pk_add_f32 v[104:105], v[104:105], v[110:111]
	v_pk_add_f32 v[106:107], v[106:107], v[108:109]
	global_store_dwordx4 v[116:117], v[104:107], off offset:64 nt
	global_load_dwordx2 v[104:105], v[120:121], off offset:256
	s_waitcnt vmcnt(0)
	v_lshlrev_b32_e32 v106, 16, v104
	v_and_b32_e32 v107, 0xffff0000, v104
	v_lshlrev_b32_e32 v104, 16, v105
	v_and_b32_e32 v105, 0xffff0000, v105
	v_pk_add_f32 v[100:101], v[100:101], v[106:107]
	v_pk_add_f32 v[102:103], v[102:103], v[104:105]
	global_store_dwordx4 v[116:117], v[100:103], off offset:512 nt
	global_load_dwordx2 v[100:101], v[120:121], off offset:288
	s_waitcnt vmcnt(0)
	v_lshlrev_b32_e32 v106, 16, v100
	v_or_b32_e32 v102, 32, v144
	v_ashrrev_i32_e32 v103, 31, v102
	v_lshlrev_b64 v[102:103], 11, v[102:103]
	v_and_b32_e32 v107, 0xffff0000, v100
	v_lshlrev_b32_e32 v100, 16, v101
	v_and_b32_e32 v101, 0xffff0000, v101
	v_lshl_add_u64 v[102:103], v[102:103], 0, v[142:143]
	v_pk_add_f32 v[92:93], v[92:93], v[106:107]
	v_pk_add_f32 v[94:95], v[94:95], v[100:101]
	v_lshl_add_u64 v[104:105], v[102:103], 1, s[20:21]
	global_store_dwordx4 v[116:117], v[92:95], off offset:576 nt
	global_load_dwordx2 v[92:93], v[104:105], off
	v_lshl_add_u64 v[100:101], v[102:103], 2, s[4:5]
	s_waitcnt vmcnt(0)
	v_lshlrev_b32_e32 v94, 16, v92
	v_and_b32_e32 v95, 0xffff0000, v92
	v_lshlrev_b32_e32 v102, 16, v93
	v_and_b32_e32 v103, 0xffff0000, v93
	v_pk_add_f32 v[92:93], v[96:97], v[94:95]
	v_pk_add_f32 v[94:95], v[98:99], v[102:103]
	global_store_dwordx4 v[100:101], v[92:95], off nt
	global_load_dwordx2 v[92:93], v[104:105], off offset:32
	s_waitcnt vmcnt(0)
	v_lshlrev_b32_e32 v94, 16, v92
	v_and_b32_e32 v95, 0xffff0000, v92
	v_lshlrev_b32_e32 v92, 16, v93
	v_and_b32_e32 v93, 0xffff0000, v93
	v_pk_add_f32 v[88:89], v[88:89], v[94:95]
	v_pk_add_f32 v[90:91], v[90:91], v[92:93]
	global_store_dwordx4 v[100:101], v[88:91], off offset:64 nt
	global_load_dwordx2 v[88:89], v[104:105], off offset:256
	s_waitcnt vmcnt(0)
	v_lshlrev_b32_e32 v90, 16, v88
	v_and_b32_e32 v91, 0xffff0000, v88
	v_lshlrev_b32_e32 v88, 16, v89
	v_and_b32_e32 v89, 0xffff0000, v89
	v_pk_add_f32 v[84:85], v[84:85], v[90:91]
	v_pk_add_f32 v[86:87], v[86:87], v[88:89]
	global_store_dwordx4 v[100:101], v[84:87], off offset:512 nt
	global_load_dwordx2 v[84:85], v[104:105], off offset:288
	s_waitcnt vmcnt(0)
	v_lshlrev_b32_e32 v90, 16, v84
	v_or_b32_e32 v86, 48, v144
	v_ashrrev_i32_e32 v87, 31, v86
	v_lshlrev_b64 v[86:87], 11, v[86:87]
	v_and_b32_e32 v91, 0xffff0000, v84
	v_lshlrev_b32_e32 v84, 16, v85
	v_and_b32_e32 v85, 0xffff0000, v85
	v_lshl_add_u64 v[86:87], v[86:87], 0, v[142:143]
	v_pk_add_f32 v[76:77], v[76:77], v[90:91]
	v_pk_add_f32 v[78:79], v[78:79], v[84:85]
	v_lshl_add_u64 v[88:89], v[86:87], 1, s[20:21]
	global_store_dwordx4 v[100:101], v[76:79], off offset:576 nt
	global_load_dwordx2 v[76:77], v[88:89], off
	v_lshl_add_u64 v[84:85], v[86:87], 2, s[4:5]
	s_waitcnt vmcnt(0)
;     __device__ __forceinline__ void operator()(const f32x4 (&acc)[2][2][4][2], const Unit& u, int wr, int wc, int fr, int fq) const {
;         const int row0 = u.pm * BM + wr * 64 + fr, col0 = u.pn * BM + wc * 32 + 4 * fq;
; #pragma unroll
;         for (int ai = 0; ai < 2; ++ai)
; #pragma unroll
;             for (int m = 0; m < 4; ++m) {
;                 const size_t off = (size_t)(row0 + ai * HALF + m * 16) * DM + col0;
; #pragma unroll
;                 for (int bj = 0; bj < 2; ++bj)
; #pragma unroll
;                     for (int n = 0; n < 2; ++n) { const u32x2 xw = *(const u32x2*)(x1b + off + bj * HALF + n * 16); f32x4 v = acc[ai][bj][m][n];
;                         v[0] += __builtin_bit_cast(float, xw.x << 16); v[1] += __builtin_bit_cast(float, xw.x & 0xffff0000u); v[2] += __builtin_bit_cast(float, xw.y << 16); v[3] += __builtin_bit_cast(float, xw.y & 0xffff0000u);
;                         __builtin_nontemporal_store(v, (f32x4*)(out + off + bj * HALF + n * 16)); }
;             }
;     }
	v_lshlrev_b32_e32 v78, 16, v76
	v_and_b32_e32 v79, 0xffff0000, v76
	v_lshlrev_b32_e32 v86, 16, v77
	v_and_b32_e32 v87, 0xffff0000, v77
	v_pk_add_f32 v[76:77], v[80:81], v[78:79]
	v_pk_add_f32 v[78:79], v[82:83], v[86:87]
	global_store_dwordx4 v[84:85], v[76:79], off nt
	global_load_dwordx2 v[76:77], v[88:89], off offset:32
	s_waitcnt vmcnt(0)
	v_lshlrev_b32_e32 v78, 16, v76
	v_and_b32_e32 v79, 0xffff0000, v76
	v_lshlrev_b32_e32 v76, 16, v77
	v_and_b32_e32 v77, 0xffff0000, v77
	v_pk_add_f32 v[72:73], v[72:73], v[78:79]
	v_pk_add_f32 v[74:75], v[74:75], v[76:77]
	global_store_dwordx4 v[84:85], v[72:75], off offset:64 nt
	global_load_dwordx2 v[72:73], v[88:89], off offset:256
	s_waitcnt vmcnt(0)
	v_lshlrev_b32_e32 v74, 16, v72
	v_and_b32_e32 v75, 0xffff0000, v72
	v_lshlrev_b32_e32 v72, 16, v73
	v_and_b32_e32 v73, 0xffff0000, v73
	v_pk_add_f32 v[68:69], v[68:69], v[74:75]
	v_pk_add_f32 v[70:71], v[70:71], v[72:73]
	global_store_dwordx4 v[84:85], v[68:71], off offset:512 nt
	global_load_dwordx2 v[68:69], v[88:89], off offset:288
	s_waitcnt vmcnt(0)
	v_lshlrev_b32_e32 v74, 16, v68
	v_and_b32_e32 v75, 0xffff0000, v68
	v_lshlrev_b32_e32 v68, 16, v69
	v_and_b32_e32 v69, 0xffff0000, v69
	v_lshl_add_u64 v[70:71], v[140:141], 0, s[14:15]
	v_pk_add_f32 v[64:65], v[64:65], v[74:75]
	v_pk_add_f32 v[66:67], v[66:67], v[68:69]
	v_lshl_add_u64 v[72:73], v[70:71], 1, s[20:21]
	global_store_dwordx4 v[84:85], v[64:67], off offset:576 nt
	global_load_dwordx2 v[64:65], v[72:73], off
	s_waitcnt vmcnt(0)
	v_lshlrev_b32_e32 v68, 16, v64
	v_and_b32_e32 v69, 0xffff0000, v64
	v_lshlrev_b32_e32 v64, 16, v65
	v_and_b32_e32 v65, 0xffff0000, v65
	v_lshl_add_u64 v[66:67], v[70:71], 2, s[4:5]
	v_pk_add_f32 v[60:61], v[60:61], v[68:69]
	v_pk_add_f32 v[62:63], v[62:63], v[64:65]
	global_store_dwordx4 v[66:67], v[60:63], off nt
	global_load_dwordx2 v[60:61], v[72:73], off offset:32
	s_waitcnt vmcnt(0)
	v_lshlrev_b32_e32 v62, 16, v60
	v_and_b32_e32 v63, 0xffff0000, v60
	v_lshlrev_b32_e32 v60, 16, v61
	v_and_b32_e32 v61, 0xffff0000, v61
	v_pk_add_f32 v[56:57], v[56:57], v[62:63]
	v_pk_add_f32 v[58:59], v[58:59], v[60:61]
	global_store_dwordx4 v[66:67], v[56:59], off offset:64 nt
	global_load_dwordx2 v[56:57], v[72:73], off offset:256
	s_waitcnt vmcnt(0)
	v_lshlrev_b32_e32 v58, 16, v56
	v_and_b32_e32 v59, 0xffff0000, v56
	v_lshlrev_b32_e32 v56, 16, v57
	v_and_b32_e32 v57, 0xffff0000, v57
	v_pk_add_f32 v[52:53], v[52:53], v[58:59]
	v_pk_add_f32 v[54:55], v[54:55], v[56:57]
	global_store_dwordx4 v[66:67], v[52:55], off offset:512 nt
	global_load_dwordx2 v[52:53], v[72:73], off offset:288
	s_waitcnt vmcnt(0)
	v_lshlrev_b32_e32 v58, 16, v52
	v_and_b32_e32 v59, 0xffff0000, v52
	v_lshlrev_b32_e32 v52, 16, v53
	v_and_b32_e32 v53, 0xffff0000, v53
	v_lshl_add_u64 v[54:55], v[140:141], 0, s[16:17]
	v_pk_add_f32 v[44:45], v[44:45], v[58:59]
	v_pk_add_f32 v[46:47], v[46:47], v[52:53]
	v_lshl_add_u64 v[56:57], v[54:55], 1, s[20:21]
	global_store_dwordx4 v[66:67], v[44:47], off offset:576 nt
	global_load_dwordx2 v[44:45], v[56:57], off
	v_lshl_add_u64 v[52:53], v[54:55], 2, s[4:5]
	s_waitcnt vmcnt(0)
	v_lshlrev_b32_e32 v46, 16, v44
	v_and_b32_e32 v47, 0xffff0000, v44
	v_lshlrev_b32_e32 v54, 16, v45
	v_and_b32_e32 v55, 0xffff0000, v45
	v_pk_add_f32 v[44:45], v[48:49], v[46:47]
	v_pk_add_f32 v[46:47], v[50:51], v[54:55]
	global_store_dwordx4 v[52:53], v[44:47], off nt
	global_load_dwordx2 v[44:45], v[56:57], off offset:32
	s_waitcnt vmcnt(0)
	v_lshlrev_b32_e32 v46, 16, v44
	v_and_b32_e32 v47, 0xffff0000, v44
	v_lshlrev_b32_e32 v44, 16, v45
	v_and_b32_e32 v45, 0xffff0000, v45
	v_pk_add_f32 v[40:41], v[40:41], v[46:47]
	v_pk_add_f32 v[42:43], v[42:43], v[44:45]
	global_store_dwordx4 v[52:53], v[40:43], off offset:64 nt
	global_load_dwordx2 v[40:41], v[56:57], off offset:256
	s_waitcnt vmcnt(0)
;     __device__ __forceinline__ void operator()(const f32x4 (&acc)[2][2][4][2], const Unit& u, int wr, int wc, int fr, int fq) const {
;         const int row0 = u.pm * BM + wr * 64 + fr, col0 = u.pn * BM + wc * 32 + 4 * fq;
; #pragma unroll
;         for (int ai = 0; ai < 2; ++ai)
; #pragma unroll
;             for (int m = 0; m < 4; ++m) {
;                 const size_t off = (size_t)(row0 + ai * HALF + m * 16) * DM + col0;
; #pragma unroll
;                 for (int bj = 0; bj < 2; ++bj)
; #pragma unroll
;                     for (int n = 0; n < 2; ++n) { const u32x2 xw = *(const u32x2*)(x1b + off + bj * HALF + n * 16); f32x4 v = acc[ai][bj][m][n];
;                         v[0] += __builtin_bit_cast(float, xw.x << 16); v[1] += __builtin_bit_cast(float, xw.x & 0xffff0000u); v[2] += __builtin_bit_cast(float, xw.y << 16); v[3] += __builtin_bit_cast(float, xw.y & 0xffff0000u);
;                         __builtin_nontemporal_store(v, (f32x4*)(out + off + bj * HALF + n * 16)); }
;             }
;     }
	v_lshlrev_b32_e32 v42, 16, v40
	v_and_b32_e32 v43, 0xffff0000, v40
	v_lshlrev_b32_e32 v40, 16, v41
	v_and_b32_e32 v41, 0xffff0000, v41
	v_pk_add_f32 v[36:37], v[36:37], v[42:43]
	v_pk_add_f32 v[38:39], v[38:39], v[40:41]
	global_store_dwordx4 v[52:53], v[36:39], off offset:512 nt
	global_load_dwordx2 v[36:37], v[56:57], off offset:288
	s_waitcnt vmcnt(0)
	v_lshlrev_b32_e32 v42, 16, v36
	v_and_b32_e32 v43, 0xffff0000, v36
	v_lshlrev_b32_e32 v36, 16, v37
	v_and_b32_e32 v37, 0xffff0000, v37
	v_lshl_add_u64 v[38:39], v[140:141], 0, s[18:19]
	v_pk_add_f32 v[28:29], v[28:29], v[42:43]
	v_pk_add_f32 v[30:31], v[30:31], v[36:37]
	v_lshl_add_u64 v[40:41], v[38:39], 1, s[20:21]
	global_store_dwordx4 v[52:53], v[28:31], off offset:576 nt
	global_load_dwordx2 v[28:29], v[40:41], off
	v_lshl_add_u64 v[36:37], v[38:39], 2, s[4:5]
	s_waitcnt vmcnt(0)
	v_lshlrev_b32_e32 v30, 16, v28
	v_and_b32_e32 v31, 0xffff0000, v28
	v_lshlrev_b32_e32 v38, 16, v29
	v_and_b32_e32 v39, 0xffff0000, v29
	v_pk_add_f32 v[28:29], v[32:33], v[30:31]
	v_pk_add_f32 v[30:31], v[34:35], v[38:39]
	global_store_dwordx4 v[36:37], v[28:31], off nt
	global_load_dwordx2 v[28:29], v[40:41], off offset:32
	s_waitcnt vmcnt(0)
	v_lshlrev_b32_e32 v30, 16, v28
	v_and_b32_e32 v31, 0xffff0000, v28
	v_lshlrev_b32_e32 v28, 16, v29
	v_and_b32_e32 v29, 0xffff0000, v29
	v_pk_add_f32 v[24:25], v[24:25], v[30:31]
	v_pk_add_f32 v[26:27], v[26:27], v[28:29]
	global_store_dwordx4 v[36:37], v[24:27], off offset:64 nt
	global_load_dwordx2 v[24:25], v[40:41], off offset:256
	s_waitcnt vmcnt(0)
	v_lshlrev_b32_e32 v26, 16, v24
	v_and_b32_e32 v27, 0xffff0000, v24
	v_lshlrev_b32_e32 v24, 16, v25
	v_and_b32_e32 v25, 0xffff0000, v25
	v_pk_add_f32 v[20:21], v[20:21], v[26:27]
	v_pk_add_f32 v[22:23], v[22:23], v[24:25]
	global_store_dwordx4 v[36:37], v[20:23], off offset:512 nt
	global_load_dwordx2 v[20:21], v[40:41], off offset:288
	s_waitcnt vmcnt(0)
	v_lshlrev_b32_e32 v26, 16, v20
	v_and_b32_e32 v27, 0xffff0000, v20
	v_lshlrev_b32_e32 v20, 16, v21
	v_and_b32_e32 v21, 0xffff0000, v21
	v_lshl_add_u64 v[22:23], v[140:141], 0, s[22:23]
	v_pk_add_f32 v[12:13], v[12:13], v[26:27]
	v_pk_add_f32 v[14:15], v[14:15], v[20:21]
	v_lshl_add_u64 v[24:25], v[22:23], 1, s[20:21]
	global_store_dwordx4 v[36:37], v[12:15], off offset:576 nt
	global_load_dwordx2 v[12:13], v[24:25], off
	v_lshl_add_u64 v[20:21], v[22:23], 2, s[4:5]
	s_waitcnt vmcnt(0)
	v_lshlrev_b32_e32 v14, 16, v12
	v_and_b32_e32 v15, 0xffff0000, v12
	v_lshlrev_b32_e32 v22, 16, v13
	v_and_b32_e32 v23, 0xffff0000, v13
	v_pk_add_f32 v[12:13], v[16:17], v[14:15]
	v_pk_add_f32 v[14:15], v[18:19], v[22:23]
	global_store_dwordx4 v[20:21], v[12:15], off nt
	global_load_dwordx2 v[12:13], v[24:25], off offset:32
	s_waitcnt vmcnt(0)
	v_lshlrev_b32_e32 v14, 16, v12
	v_and_b32_e32 v15, 0xffff0000, v12
	v_lshlrev_b32_e32 v12, 16, v13
	v_and_b32_e32 v13, 0xffff0000, v13
	v_pk_add_f32 v[8:9], v[8:9], v[14:15]
	v_pk_add_f32 v[10:11], v[10:11], v[12:13]
	global_store_dwordx4 v[20:21], v[8:11], off offset:64 nt
	global_load_dwordx2 v[8:9], v[24:25], off offset:256
	s_waitcnt vmcnt(0)
	v_lshlrev_b32_e32 v10, 16, v8
	v_and_b32_e32 v11, 0xffff0000, v8
	v_lshlrev_b32_e32 v8, 16, v9
	v_and_b32_e32 v9, 0xffff0000, v9
	v_pk_add_f32 v[4:5], v[4:5], v[10:11]
	v_pk_add_f32 v[6:7], v[6:7], v[8:9]
	global_store_dwordx4 v[20:21], v[4:7], off offset:512 nt
	global_load_dwordx2 v[4:5], v[24:25], off offset:288
	s_waitcnt vmcnt(0)
	v_lshlrev_b32_e32 v6, 16, v4
	v_and_b32_e32 v7, 0xffff0000, v4
	v_lshlrev_b32_e32 v4, 16, v5
	v_and_b32_e32 v5, 0xffff0000, v5
	v_pk_add_f32 v[0:1], v[0:1], v[6:7]
	v_pk_add_f32 v[2:3], v[2:3], v[4:5]
	global_store_dwordx4 v[20:21], v[0:3], off offset:576 nt
	s_cbranch_vccnz .LBB0_1153
	s_andn2_b64 vcc, exec, s[2:3]
	s_cbranch_vccnz .LBB0_1152
	s_barrier
	s_branch .LBB0_1152
